# P0: memn gain chunks and W_in item gains requested up front instead of one dependent round trip each; redundant waits between kernarg pointer loads dropped
# baseline (speedup 1.0000x reference)
; #define LAS __attribute__((address_space(3)))
; #define g_mix ARGP(2)
; #define w_in ARGP(3)
; __device__ __forceinline__ void p0_transpose64(const float* W, int ldw, int K, const float* gain, bf16_t* WT, int nblk, int ncol_src0, int row_off, LAS float* scr, int item, int lane) {
;     const int kb = item / nblk, nb = item % nblk, k0 = 64 * kb, n0 = 64 * nb;
;     const int c4 = (lane & 15) * 4, kr = lane >> 4;
;     f32x4 w[16];
; #pragma unroll
;     for (int i = 0; i < 16; ++i) w[i] = __builtin_nontemporal_load((const f32x4*)(W + (size_t)(k0 + kr + 4 * i) * ldw + ncol_src0 + n0 + c4));
; #pragma unroll
;     for (int i = 0; i < 16; ++i) { f32x4 v = w[i]; if (gain) v = v * gain[k0 + kr + 4 * i]; *(LAS f32x4*)(scr + (kr + 4 * i) * 68 + c4) = v; }
; __global__ void __launch_bounds__(NWAVES * 64, 2) fwd(Args args) {
;     ...
;             for (int it = (bx - NQB) * NWAVES + F.wave; it < I_INL; it += (256 - NQB) * NWAVES) { const int kb = it / (IN_Q0 / 64), nb = it % (IN_Q0 / 64);
;                 p0_transpose64(w_in, INW, DM, g_mix, W_inT, IN_N / 64, (nb * 64 >= 4096) ? 16 : 0, 0, scr, kb * (IN_N / 64) + nb, F.lane); }
.LBB0_16:
	flat_load_dwordx2 v[2:3], v[70:71] offset:24 sc0 sc1
	s_waitcnt vmcnt(0)
	s_mul_hi_i32 s4, s3, 0x2aaaaaab
	s_lshr_b32 s6, s4, 31
	s_ashr_i32 s4, s4, 4
	s_add_i32 s4, s4, s6
	s_mul_i32 s6, s4, 0x60
	s_mulk_i32 s4, 0xffa0
	s_add_i32 s4, s3, s4
	s_cmp_gt_i32 s4, 63
	s_cselect_b32 s4, 64, 0
	s_add_i32 s7, s3, s6
	s_mul_hi_i32 s7, s7, 0x2aaaaaab
	s_lshr_b32 s10, s7, 31
	s_ashr_i32 s7, s7, 5
	s_add_i32 s7, s7, s10
	s_mul_i32 s11, s7, 0xc0
	s_sub_i32 s6, s6, s11
	s_add_i32 s6, s3, s6
	s_lshl_b32 s6, s6, 6
	s_lshl_b32 s10, s7, 6
	s_ashr_i32 s7, s6, 31
	v_or_b32_e32 v86, s10, v74
	v_or_b32_e32 v6, 4, v86
	v_or_b32_e32 v8, 8, v86
	v_or_b32_e32 v10, 12, v86
	v_or_b32_e32 v11, 16, v86
	v_or_b32_e32 v12, 20, v86
	v_or_b32_e32 v13, 24, v86
	v_or_b32_e32 v14, 28, v86
	v_or_b32_e32 v15, 32, v86
	v_or_b32_e32 v16, 36, v86
	v_or_b32_e32 v17, 40, v86
	v_or_b32_e32 v18, 44, v86
	v_or_b32_e32 v19, 48, v86
	v_or_b32_e32 v20, 52, v86
	v_or_b32_e32 v21, 56, v86
	flat_load_dwordx2 v[72:73], v[70:71] offset:16 sc0 sc1
	s_waitcnt vmcnt(0)
	v_or_b32_e32 v85, 60, v86
	v_ashrrev_i32_e32 v87, 31, v86
	s_waitcnt lgkmcnt(0)
	v_lshl_add_u64 v[2:3], v[2:3], 0, s[4:5]
	v_lshl_add_u64 v[2:3], s[6:7], 2, v[2:3]
	v_lshl_add_u64 v[2:3], v[2:3], 0, v[66:67]
	v_mad_i64_i32 v[4:5], s[12:13], v86, s15, v[2:3]
	v_mad_i64_i32 v[6:7], s[12:13], v6, s15, v[2:3]
	v_mad_i64_i32 v[8:9], s[12:13], v8, s15, v[2:3]
	v_mad_i64_i32 v[88:89], s[12:13], v10, s15, v[2:3]
	v_mad_i64_i32 v[90:91], s[12:13], v11, s15, v[2:3]
	v_mad_i64_i32 v[92:93], s[12:13], v12, s15, v[2:3]
	v_mad_i64_i32 v[94:95], s[12:13], v13, s15, v[2:3]
	v_mad_i64_i32 v[96:97], s[12:13], v14, s15, v[2:3]
	v_mad_i64_i32 v[98:99], s[12:13], v15, s15, v[2:3]
	v_mad_i64_i32 v[100:101], s[12:13], v16, s15, v[2:3]
	v_mad_i64_i32 v[102:103], s[12:13], v17, s15, v[2:3]
	v_mad_i64_i32 v[104:105], s[12:13], v18, s15, v[2:3]
	v_mad_i64_i32 v[106:107], s[12:13], v19, s15, v[2:3]
	v_mad_i64_i32 v[108:109], s[12:13], v20, s15, v[2:3]
	v_mad_i64_i32 v[110:111], s[12:13], v21, s15, v[2:3]
	flat_load_dwordx4 v[62:65], v[4:5] nt
	flat_load_dwordx4 v[58:61], v[6:7] nt
	flat_load_dwordx4 v[54:57], v[8:9] nt
	flat_load_dwordx4 v[50:53], v[88:89] nt
	flat_load_dwordx4 v[46:49], v[90:91] nt
	flat_load_dwordx4 v[42:45], v[92:93] nt
	flat_load_dwordx4 v[38:41], v[94:95] nt
	flat_load_dwordx4 v[34:37], v[96:97] nt
	flat_load_dwordx4 v[30:33], v[98:99] nt
	flat_load_dwordx4 v[26:29], v[100:101] nt
	flat_load_dwordx4 v[22:25], v[102:103] nt
	flat_load_dwordx4 v[18:21], v[104:105] nt
	flat_load_dwordx4 v[14:17], v[106:107] nt
	flat_load_dwordx4 v[10:13], v[108:109] nt
	v_mad_i64_i32 v[88:89], s[12:13], v85, s15, v[2:3]
	flat_load_dwordx4 v[6:9], v[110:111] nt
	flat_load_dwordx4 v[2:5], v[88:89] nt
	v_cmp_ne_u64_e32 vcc, 0, v[72:73]
	v_lshl_add_u64 v[72:73], v[86:87], 2, v[72:73]
	s_and_saveexec_b64 s[12:13], vcc
	s_xor_b64 s[12:13], exec, s[12:13]
	s_cbranch_execz .LBB0_18
	global_load_dword v220, v[72:73], off
	global_load_dword v221, v[72:73], off offset:16
	global_load_dword v222, v[72:73], off offset:32
	global_load_dword v223, v[72:73], off offset:48
	global_load_dword v224, v[72:73], off offset:64
	global_load_dword v225, v[72:73], off offset:80
	global_load_dword v226, v[72:73], off offset:96
	global_load_dword v227, v[72:73], off offset:112
	global_load_dword v228, v[72:73], off offset:128
	global_load_dword v229, v[72:73], off offset:144
	global_load_dword v230, v[72:73], off offset:160
	global_load_dword v231, v[72:73], off offset:176
	global_load_dword v232, v[72:73], off offset:192
	global_load_dword v233, v[72:73], off offset:208
	global_load_dword v234, v[72:73], off offset:224
	global_load_dword v235, v[72:73], off offset:240
	s_waitcnt vmcnt(0) lgkmcnt(0)
	v_mov_b32_e32 v86, v220
	v_pk_mul_f32 v[64:65], v[64:65], v[86:87] op_sel_hi:[1,0]
	v_pk_mul_f32 v[62:63], v[62:63], v[86:87] op_sel_hi:[1,0]
	ds_write_b128 v84, v[62:65]
	s_nop 1
	v_mov_b32_e32 v62, v221
	v_pk_mul_f32 v[60:61], v[60:61], v[62:63] op_sel_hi:[1,0]
	v_pk_mul_f32 v[58:59], v[58:59], v[62:63] op_sel_hi:[1,0]

; #define LAS __attribute__((address_space(3)))
; #define LDS_WAIT() asm volatile("s_waitcnt lgkmcnt(0)" ::: "memory")
; __device__ __forceinline__ void p0_transpose64(const float* W, int ldw, int K, const float* gain, bf16_t* WT, int nblk, int ncol_src0, int row_off, LAS float* scr, int item, int lane) {
;     ...
; #pragma unroll
;     for (int i = 0; i < 16; ++i) w[i] = __builtin_nontemporal_load((const f32x4*)(W + (size_t)(k0 + kr + 4 * i) * ldw + ncol_src0 + n0 + c4));
; #pragma unroll
;     for (int i = 0; i < 16; ++i) { f32x4 v = w[i]; if (gain) v = v * gain[k0 + kr + 4 * i]; *(LAS f32x4*)(scr + (kr + 4 * i) * 68 + c4) = v; }
;     LDS_WAIT(); asm volatile("" ::: "memory");
.LBB0_20:
	s_or_b64 exec, exec, s[12:13]
	s_waitcnt vmcnt(0) lgkmcnt(0)
	ds_write_b128 v84, v[58:61] offset:8704
	s_and_saveexec_b64 s[12:13], vcc
	s_xor_b64 s[12:13], exec, s[12:13]
	s_cbranch_execz .LBB0_22
	s_nop 1
	v_mov_b32_e32 v58, v222
	v_pk_mul_f32 v[56:57], v[56:57], v[58:59] op_sel_hi:[1,0]
	v_pk_mul_f32 v[54:55], v[54:55], v[58:59] op_sel_hi:[1,0]
	ds_write_b128 v84, v[54:57] offset:272
	s_nop 1
	v_mov_b32_e32 v54, v223
	v_pk_mul_f32 v[52:53], v[52:53], v[54:55] op_sel_hi:[1,0]
	v_pk_mul_f32 v[50:51], v[50:51], v[54:55] op_sel_hi:[1,0]
.LBB0_22:
	s_andn2_saveexec_b64 s[12:13], s[12:13]
	ds_write_b128 v84, v[54:57] offset:272
	s_or_b64 exec, exec, s[12:13]
	ds_write_b128 v84, v[50:53] offset:8976
	s_and_saveexec_b64 s[12:13], vcc
	s_xor_b64 s[12:13], exec, s[12:13]
	s_cbranch_execz .LBB0_26
	s_nop 1
	v_mov_b32_e32 v50, v224
	v_pk_mul_f32 v[48:49], v[48:49], v[50:51] op_sel_hi:[1,0]
	v_pk_mul_f32 v[46:47], v[46:47], v[50:51] op_sel_hi:[1,0]
	ds_write_b128 v84, v[46:49] offset:544
	s_nop 1
	v_mov_b32_e32 v46, v225
	v_pk_mul_f32 v[44:45], v[44:45], v[46:47] op_sel_hi:[1,0]
	v_pk_mul_f32 v[42:43], v[42:43], v[46:47] op_sel_hi:[1,0]
.LBB0_26:
	s_andn2_saveexec_b64 s[12:13], s[12:13]
	ds_write_b128 v84, v[46:49] offset:544
	s_or_b64 exec, exec, s[12:13]
	ds_write_b128 v84, v[42:45] offset:9248
	s_and_saveexec_b64 s[12:13], vcc
	s_xor_b64 s[12:13], exec, s[12:13]
	s_cbranch_execz .LBB0_30
	s_nop 1
	v_mov_b32_e32 v42, v226
	v_pk_mul_f32 v[40:41], v[40:41], v[42:43] op_sel_hi:[1,0]
	v_pk_mul_f32 v[38:39], v[38:39], v[42:43] op_sel_hi:[1,0]
	ds_write_b128 v84, v[38:41] offset:816
	s_nop 1
	v_mov_b32_e32 v38, v227
	v_pk_mul_f32 v[36:37], v[36:37], v[38:39] op_sel_hi:[1,0]
	v_pk_mul_f32 v[34:35], v[34:35], v[38:39] op_sel_hi:[1,0]
.LBB0_30:
	s_andn2_saveexec_b64 s[12:13], s[12:13]
	ds_write_b128 v84, v[38:41] offset:816
	s_or_b64 exec, exec, s[12:13]
	ds_write_b128 v84, v[34:37] offset:9520
	s_and_saveexec_b64 s[12:13], vcc
	s_xor_b64 s[12:13], exec, s[12:13]
	s_cbranch_execz .LBB0_34
	s_nop 1
	v_mov_b32_e32 v34, v228
	v_pk_mul_f32 v[32:33], v[32:33], v[34:35] op_sel_hi:[1,0]
	v_pk_mul_f32 v[30:31], v[30:31], v[34:35] op_sel_hi:[1,0]
	ds_write_b128 v84, v[30:33] offset:1088
	s_nop 1
	v_mov_b32_e32 v30, v229
	v_pk_mul_f32 v[28:29], v[28:29], v[30:31] op_sel_hi:[1,0]
	v_pk_mul_f32 v[26:27], v[26:27], v[30:31] op_sel_hi:[1,0]
.LBB0_34:
	s_andn2_saveexec_b64 s[12:13], s[12:13]
	ds_write_b128 v84, v[30:33] offset:1088
	s_or_b64 exec, exec, s[12:13]
	ds_write_b128 v84, v[26:29] offset:9792
	s_and_saveexec_b64 s[12:13], vcc
	s_xor_b64 s[12:13], exec, s[12:13]
	s_cbranch_execz .LBB0_38
	s_nop 1
	v_mov_b32_e32 v26, v230
	v_pk_mul_f32 v[24:25], v[24:25], v[26:27] op_sel_hi:[1,0]
	v_pk_mul_f32 v[22:23], v[22:23], v[26:27] op_sel_hi:[1,0]
	ds_write_b128 v84, v[22:25] offset:1360
	s_nop 1
	v_mov_b32_e32 v22, v231
	v_pk_mul_f32 v[20:21], v[20:21], v[22:23] op_sel_hi:[1,0]
	v_pk_mul_f32 v[18:19], v[18:19], v[22:23] op_sel_hi:[1,0]
.LBB0_38:
	s_andn2_saveexec_b64 s[12:13], s[12:13]
	ds_write_b128 v84, v[22:25] offset:1360
	s_or_b64 exec, exec, s[12:13]
	ds_write_b128 v84, v[18:21] offset:10064
	s_and_saveexec_b64 s[12:13], vcc
	s_xor_b64 s[12:13], exec, s[12:13]
	s_cbranch_execz .LBB0_42
	s_nop 1
	v_mov_b32_e32 v18, v232
	v_pk_mul_f32 v[16:17], v[16:17], v[18:19] op_sel_hi:[1,0]
	v_pk_mul_f32 v[14:15], v[14:15], v[18:19] op_sel_hi:[1,0]
	ds_write_b128 v84, v[14:17] offset:1632
	s_nop 1
	v_mov_b32_e32 v14, v233
	v_pk_mul_f32 v[12:13], v[12:13], v[14:15] op_sel_hi:[1,0]
	v_pk_mul_f32 v[10:11], v[10:11], v[14:15] op_sel_hi:[1,0]
.LBB0_42:
	s_andn2_saveexec_b64 s[12:13], s[12:13]
	ds_write_b128 v84, v[14:17] offset:1632
	s_or_b64 exec, exec, s[12:13]
	ds_write_b128 v84, v[10:13] offset:10336
	s_and_saveexec_b64 s[12:13], vcc
	s_xor_b64 s[12:13], exec, s[12:13]
	s_cbranch_execz .LBB0_46
	s_nop 1
	v_mov_b32_e32 v10, v234
	v_pk_mul_f32 v[8:9], v[8:9], v[10:11] op_sel_hi:[1,0]
	v_pk_mul_f32 v[6:7], v[6:7], v[10:11] op_sel_hi:[1,0]
	ds_write_b128 v84, v[6:9] offset:1904
	s_nop 1
	v_mov_b32_e32 v6, v235
	v_pk_mul_f32 v[4:5], v[4:5], v[6:7] op_sel_hi:[1,0]
	v_pk_mul_f32 v[2:3], v[2:3], v[6:7] op_sel_hi:[1,0]

; #define LAS __attribute__((address_space(3)))
; __device__ __forceinline__ void p0_load(const P0Item& it, f32x4 (&w)[16], int lane) {
;     const unsigned voff = (unsigned)(((lane >> 4) * it.ldw + (lane & 15) * 4) * 4);
; #pragma unroll
;     for (int i = 0; i < 16; ++i) w[i] = __builtin_nontemporal_load((const f32x4*)((const char*)(it.src + (size_t)(4 * i) * it.ldw) + voff));
; }
; __device__ __forceinline__ void p0_finish(const P0Item& it, const f32x4 (&w)[16], LAS float* scr, int lane) {
;     const int c4 = (lane & 15) * 4, kr = lane >> 4;
;     if (it.gain) { const unsigned goff = (unsigned)(kr * 4);
; #pragma unroll
;         for (int i = 0; i < 16; ++i) { const float g = *(const float*)((const char*)(it.gain + 4 * i) + goff); *(LAS f32x4*)(scr + (kr + 4 * i) * 68 + c4) = w[i] * g; } }
; template <class F> __device__ __forceinline__ void p0_pipe(int n, F desc, LAS float* scr, int lane) {
;     ...
;     for (int j = 0; j < n; j += 2) {
;         const bool hb_ = j + 1 < n; if (hb_) { b = desc(j + 1); p0_load(b, w1, lane); }
;         p0_finish(a, w0, scr, lane);
;         if (!hb_) break;
;         if (j + 2 < n) { a = desc(j + 2); p0_load(a, w0, lane); }
;         p0_finish(b, w1, scr, lane);
.LBB0_52:
	s_add_i32 s14, s10, 0xfffffa00
	s_mul_hi_i32 s15, s14, 0x2aaaaaab
	s_lshr_b32 s16, s15, 31
	s_ashr_i32 s15, s15, 5
	s_add_i32 s15, s15, s16
	s_mul_i32 s16, s15, 0xc0
	s_sub_i32 s16, s14, s16
	s_lshl_b32 s14, s15, 6
	s_lshl_b32 s16, s16, 6
	v_mad_i64_i32 v[66:67], s[18:19], s14, v148, v[142:143]
	s_ashr_i32 s17, s16, 31
	v_lshl_add_u64 v[66:67], s[16:17], 2, v[66:67]
	v_lshl_add_u64 v[66:67], v[66:67], 0, v[134:135]
	v_add_co_u32_e32 v68, vcc, s3, v66
	s_nop 1
	v_addc_co_u32_e32 v69, vcc, 0, v67, vcc
	flat_load_dwordx4 v[126:129], v[66:67] nt
	flat_load_dwordx4 v[122:125], v[68:69] offset:256 nt
	v_add_co_u32_e32 v68, vcc, s22, v66
	s_nop 1
	v_addc_co_u32_e32 v69, vcc, 0, v67, vcc
	v_add_co_u32_e32 v70, vcc, s23, v66
	s_nop 1
	v_addc_co_u32_e32 v71, vcc, 0, v67, vcc
	flat_load_dwordx4 v[118:121], v[68:69] offset:512 nt
	flat_load_dwordx4 v[114:117], v[70:71] offset:768 nt
	v_add_co_u32_e32 v68, vcc, s24, v66
	s_nop 1
	v_addc_co_u32_e32 v69, vcc, 0, v67, vcc
	v_add_co_u32_e32 v70, vcc, s25, v66
	s_nop 1
	v_addc_co_u32_e32 v71, vcc, 0, v67, vcc
	flat_load_dwordx4 v[110:113], v[68:69] offset:1024 nt
	flat_load_dwordx4 v[106:109], v[70:71] offset:1280 nt
	v_add_co_u32_e32 v68, vcc, s26, v66
	s_nop 1
	v_addc_co_u32_e32 v69, vcc, 0, v67, vcc
	v_add_co_u32_e32 v70, vcc, s27, v66
	s_nop 1
	v_addc_co_u32_e32 v71, vcc, 0, v67, vcc
	flat_load_dwordx4 v[102:105], v[68:69] offset:1536 nt
	flat_load_dwordx4 v[98:101], v[70:71] offset:1792 nt
	v_add_co_u32_e32 v68, vcc, s28, v66
	s_nop 1
	v_addc_co_u32_e32 v69, vcc, 0, v67, vcc
	v_add_co_u32_e32 v70, vcc, s29, v66
	s_nop 1
	v_addc_co_u32_e32 v71, vcc, 0, v67, vcc
	flat_load_dwordx4 v[94:97], v[68:69] offset:2048 nt
	flat_load_dwordx4 v[90:93], v[70:71] offset:2304 nt
	v_add_co_u32_e32 v68, vcc, s30, v66
	s_nop 1
	v_addc_co_u32_e32 v69, vcc, 0, v67, vcc
	v_add_co_u32_e32 v70, vcc, s31, v66
	s_nop 1
	v_addc_co_u32_e32 v71, vcc, 0, v67, vcc
	flat_load_dwordx4 v[86:89], v[68:69] offset:2560 nt
	flat_load_dwordx4 v[82:85], v[70:71] offset:2816 nt
	v_add_co_u32_e32 v68, vcc, s33, v66
	s_nop 1
	v_addc_co_u32_e32 v69, vcc, 0, v67, vcc
	v_add_co_u32_e32 v70, vcc, 0x270000, v66
	s_nop 1
	v_addc_co_u32_e32 v71, vcc, 0, v67, vcc
	flat_load_dwordx4 v[78:81], v[68:69] offset:3072 nt
	flat_load_dwordx4 v[74:77], v[70:71] offset:3328 nt
	v_add_co_u32_e32 v68, vcc, 0x2a0000, v66
	s_nop 1
	v_addc_co_u32_e32 v69, vcc, 0, v67, vcc
	v_add_co_u32_e32 v66, vcc, 0x2d0000, v66
	s_nop 1
	v_addc_co_u32_e32 v67, vcc, 0, v67, vcc
	flat_load_dwordx4 v[70:73], v[68:69] offset:3584 nt
	s_nop 0
	flat_load_dwordx4 v[66:69], v[66:67] offset:3840 nt
	v_cmp_ne_u64_e32 vcc, 0, v[146:147]
	s_and_saveexec_b64 s[18:19], vcc
	s_xor_b64 s[18:19], exec, s[18:19]
	s_cbranch_execz .LBB0_54
	v_lshl_add_u64 v[152:153], v[146:147], 0, v[138:139]
	global_load_dword v200, v[152:153], off
	global_load_dword v201, v[152:153], off offset:16
	global_load_dword v202, v[152:153], off offset:32
	global_load_dword v203, v[152:153], off offset:48
	global_load_dword v204, v[152:153], off offset:64
	global_load_dword v205, v[152:153], off offset:80
	global_load_dword v206, v[152:153], off offset:96
	global_load_dword v207, v[152:153], off offset:112
	global_load_dword v208, v[152:153], off offset:128
	global_load_dword v209, v[152:153], off offset:144
	global_load_dword v210, v[152:153], off offset:160
	global_load_dword v211, v[152:153], off offset:176
	global_load_dword v212, v[152:153], off offset:192
	global_load_dword v213, v[152:153], off offset:208
	global_load_dword v214, v[152:153], off offset:224
	global_load_dword v215, v[152:153], off offset:240
	s_waitcnt vmcnt(0) lgkmcnt(0)
	v_mov_b32_e32 v130, v200
	v_pk_mul_f32 v[132:133], v[4:5], v[130:131] op_sel_hi:[1,0]
	v_pk_mul_f32 v[130:131], v[2:3], v[130:131] op_sel_hi:[1,0]
	ds_write_b128 v150, v[130:133]
	s_nop 1
	v_mov_b32_e32 v130, v201
	v_pk_mul_f32 v[132:133], v[8:9], v[130:131] op_sel_hi:[1,0]
	v_pk_mul_f32 v[130:131], v[6:7], v[130:131] op_sel_hi:[1,0]
	ds_write_b128 v150, v[130:133] offset:8704
	s_nop 1
	v_mov_b32_e32 v130, v202
	v_pk_mul_f32 v[132:133], v[12:13], v[130:131] op_sel_hi:[1,0]
	v_pk_mul_f32 v[130:131], v[10:11], v[130:131] op_sel_hi:[1,0]
	ds_write_b128 v150, v[130:133] offset:272
	s_nop 1
	v_mov_b32_e32 v130, v203
	v_pk_mul_f32 v[132:133], v[16:17], v[130:131] op_sel_hi:[1,0]
	v_pk_mul_f32 v[130:131], v[14:15], v[130:131] op_sel_hi:[1,0]
	ds_write_b128 v150, v[130:133] offset:8976
	s_nop 1
	v_mov_b32_e32 v130, v204
	v_pk_mul_f32 v[132:133], v[20:21], v[130:131] op_sel_hi:[1,0]
	v_pk_mul_f32 v[130:131], v[18:19], v[130:131] op_sel_hi:[1,0]
	ds_write_b128 v150, v[130:133] offset:544
	s_nop 1
	v_mov_b32_e32 v130, v205
	v_pk_mul_f32 v[132:133], v[24:25], v[130:131] op_sel_hi:[1,0]
	v_pk_mul_f32 v[130:131], v[22:23], v[130:131] op_sel_hi:[1,0]
	ds_write_b128 v150, v[130:133] offset:9248
	s_nop 1
	v_mov_b32_e32 v130, v206
	v_pk_mul_f32 v[132:133], v[28:29], v[130:131] op_sel_hi:[1,0]
	v_pk_mul_f32 v[130:131], v[26:27], v[130:131] op_sel_hi:[1,0]
	ds_write_b128 v150, v[130:133] offset:816
	s_nop 1
	v_mov_b32_e32 v130, v207
	v_pk_mul_f32 v[132:133], v[32:33], v[130:131] op_sel_hi:[1,0]
	v_pk_mul_f32 v[130:131], v[30:31], v[130:131] op_sel_hi:[1,0]
	ds_write_b128 v150, v[130:133] offset:9520
	s_nop 1
	v_mov_b32_e32 v130, v208
	v_pk_mul_f32 v[132:133], v[36:37], v[130:131] op_sel_hi:[1,0]
	v_pk_mul_f32 v[130:131], v[34:35], v[130:131] op_sel_hi:[1,0]
	ds_write_b128 v150, v[130:133] offset:1088
	s_nop 1
	v_mov_b32_e32 v130, v209
	v_pk_mul_f32 v[132:133], v[40:41], v[130:131] op_sel_hi:[1,0]
	v_pk_mul_f32 v[130:131], v[38:39], v[130:131] op_sel_hi:[1,0]
	ds_write_b128 v150, v[130:133] offset:9792
	s_nop 1
	v_mov_b32_e32 v130, v210
	v_pk_mul_f32 v[132:133], v[44:45], v[130:131] op_sel_hi:[1,0]
	v_pk_mul_f32 v[130:131], v[42:43], v[130:131] op_sel_hi:[1,0]
	ds_write_b128 v150, v[130:133] offset:1360
	s_nop 1
	v_mov_b32_e32 v130, v211
	v_pk_mul_f32 v[132:133], v[48:49], v[130:131] op_sel_hi:[1,0]
	v_pk_mul_f32 v[130:131], v[46:47], v[130:131] op_sel_hi:[1,0]
	ds_write_b128 v150, v[130:133] offset:10064
	s_nop 1
	v_mov_b32_e32 v130, v212
	v_pk_mul_f32 v[132:133], v[52:53], v[130:131] op_sel_hi:[1,0]
	v_pk_mul_f32 v[130:131], v[50:51], v[130:131] op_sel_hi:[1,0]
	ds_write_b128 v150, v[130:133] offset:1632
	s_nop 1
	v_mov_b32_e32 v130, v213
	v_pk_mul_f32 v[132:133], v[56:57], v[130:131] op_sel_hi:[1,0]
	v_pk_mul_f32 v[130:131], v[54:55], v[130:131] op_sel_hi:[1,0]
	ds_write_b128 v150, v[130:133] offset:10336
	s_nop 1
	v_mov_b32_e32 v130, v214
	v_pk_mul_f32 v[132:133], v[60:61], v[130:131] op_sel_hi:[1,0]
	v_pk_mul_f32 v[130:131], v[58:59], v[130:131] op_sel_hi:[1,0]
	ds_write_b128 v150, v[130:133] offset:1904
	s_nop 1
	v_mov_b32_e32 v130, v215
	v_pk_mul_f32 v[132:133], v[64:65], v[130:131] op_sel_hi:[1,0]
	v_pk_mul_f32 v[130:131], v[62:63], v[130:131] op_sel_hi:[1,0]

; #define LAS __attribute__((address_space(3)))
; __device__ __forceinline__ void p0_finish(const P0Item& it, const f32x4 (&w)[16], LAS float* scr, int lane) {
;     const int c4 = (lane & 15) * 4, kr = lane >> 4;
;     if (it.gain) { const unsigned goff = (unsigned)(kr * 4);
; #pragma unroll
;         for (int i = 0; i < 16; ++i) { const float g = *(const float*)((const char*)(it.gain + 4 * i) + goff); *(LAS f32x4*)(scr + (kr + 4 * i) * 68 + c4) = w[i] * g; } }
; template <class F> __device__ __forceinline__ void p0_pipe(int n, F desc, LAS float* scr, int lane) {
;     ...
;         p0_finish(b, w1, scr, lane);
.LBB0_60:
	v_lshl_add_u64 v[152:153], s[14:15], 2, v[144:145]
	global_load_dword v184, v[152:153], off
	global_load_dword v185, v[152:153], off offset:16
	global_load_dword v186, v[152:153], off offset:32
	global_load_dword v187, v[152:153], off offset:48
	global_load_dword v188, v[152:153], off offset:64
	global_load_dword v189, v[152:153], off offset:80
	global_load_dword v190, v[152:153], off offset:96
	global_load_dword v191, v[152:153], off offset:112
	global_load_dword v192, v[152:153], off offset:128
	global_load_dword v193, v[152:153], off offset:144
	global_load_dword v194, v[152:153], off offset:160
	global_load_dword v195, v[152:153], off offset:176
	global_load_dword v196, v[152:153], off offset:192
	global_load_dword v197, v[152:153], off offset:208
	global_load_dword v198, v[152:153], off offset:224
	global_load_dword v199, v[152:153], off offset:240
	s_waitcnt vmcnt(0) lgkmcnt(0)
	v_mov_b32_e32 v154, v184
	v_pk_mul_f32 v[128:129], v[128:129], v[154:155] op_sel_hi:[1,0]
	v_pk_mul_f32 v[126:127], v[126:127], v[154:155] op_sel_hi:[1,0]
	ds_write_b128 v150, v[126:129]
	s_nop 1
	v_mov_b32_e32 v126, v185
	v_pk_mul_f32 v[124:125], v[124:125], v[126:127] op_sel_hi:[1,0]
	v_pk_mul_f32 v[122:123], v[122:123], v[126:127] op_sel_hi:[1,0]
	ds_write_b128 v150, v[122:125] offset:8704
	s_nop 1
	v_mov_b32_e32 v122, v186
	v_pk_mul_f32 v[120:121], v[120:121], v[122:123] op_sel_hi:[1,0]
	v_pk_mul_f32 v[118:119], v[118:119], v[122:123] op_sel_hi:[1,0]
	ds_write_b128 v150, v[118:121] offset:272
	s_nop 1
	v_mov_b32_e32 v118, v187
	v_pk_mul_f32 v[116:117], v[116:117], v[118:119] op_sel_hi:[1,0]
	v_pk_mul_f32 v[114:115], v[114:115], v[118:119] op_sel_hi:[1,0]
	ds_write_b128 v150, v[114:117] offset:8976
	s_nop 1
	v_mov_b32_e32 v114, v188
	v_pk_mul_f32 v[112:113], v[112:113], v[114:115] op_sel_hi:[1,0]
	v_pk_mul_f32 v[110:111], v[110:111], v[114:115] op_sel_hi:[1,0]
	ds_write_b128 v150, v[110:113] offset:544
	s_nop 1
	v_mov_b32_e32 v110, v189
	v_pk_mul_f32 v[108:109], v[108:109], v[110:111] op_sel_hi:[1,0]
	v_pk_mul_f32 v[106:107], v[106:107], v[110:111] op_sel_hi:[1,0]
	ds_write_b128 v150, v[106:109] offset:9248
	s_nop 1
	v_mov_b32_e32 v106, v190
	v_pk_mul_f32 v[104:105], v[104:105], v[106:107] op_sel_hi:[1,0]
	v_pk_mul_f32 v[102:103], v[102:103], v[106:107] op_sel_hi:[1,0]
	ds_write_b128 v150, v[102:105] offset:816
	s_nop 1
	v_mov_b32_e32 v102, v191
	v_pk_mul_f32 v[100:101], v[100:101], v[102:103] op_sel_hi:[1,0]
	v_pk_mul_f32 v[98:99], v[98:99], v[102:103] op_sel_hi:[1,0]
	ds_write_b128 v150, v[98:101] offset:9520
	s_nop 1
	v_mov_b32_e32 v98, v192
	v_pk_mul_f32 v[96:97], v[96:97], v[98:99] op_sel_hi:[1,0]
	v_pk_mul_f32 v[94:95], v[94:95], v[98:99] op_sel_hi:[1,0]
	ds_write_b128 v150, v[94:97] offset:1088
	s_nop 1
	v_mov_b32_e32 v94, v193
	v_pk_mul_f32 v[92:93], v[92:93], v[94:95] op_sel_hi:[1,0]
	v_pk_mul_f32 v[90:91], v[90:91], v[94:95] op_sel_hi:[1,0]
	ds_write_b128 v150, v[90:93] offset:9792
	s_nop 1
	v_mov_b32_e32 v90, v194
	v_pk_mul_f32 v[88:89], v[88:89], v[90:91] op_sel_hi:[1,0]
	v_pk_mul_f32 v[86:87], v[86:87], v[90:91] op_sel_hi:[1,0]
	ds_write_b128 v150, v[86:89] offset:1360
	s_nop 1
	v_mov_b32_e32 v86, v195
	v_pk_mul_f32 v[84:85], v[84:85], v[86:87] op_sel_hi:[1,0]
	v_pk_mul_f32 v[82:83], v[82:83], v[86:87] op_sel_hi:[1,0]
	ds_write_b128 v150, v[82:85] offset:10064
	s_nop 1
	v_mov_b32_e32 v82, v196
	v_pk_mul_f32 v[80:81], v[80:81], v[82:83] op_sel_hi:[1,0]
	v_pk_mul_f32 v[78:79], v[78:79], v[82:83] op_sel_hi:[1,0]
	ds_write_b128 v150, v[78:81] offset:1632
	s_nop 1
	v_mov_b32_e32 v78, v197
	v_pk_mul_f32 v[76:77], v[76:77], v[78:79] op_sel_hi:[1,0]
	v_pk_mul_f32 v[74:75], v[74:75], v[78:79] op_sel_hi:[1,0]
	ds_write_b128 v150, v[74:77] offset:10336
	s_nop 1
	v_mov_b32_e32 v74, v198
	v_pk_mul_f32 v[72:73], v[72:73], v[74:75] op_sel_hi:[1,0]
	v_pk_mul_f32 v[70:71], v[70:71], v[74:75] op_sel_hi:[1,0]
	ds_write_b128 v150, v[70:73] offset:1904
	s_nop 1
	v_mov_b32_e32 v70, v199
	v_pk_mul_f32 v[68:69], v[68:69], v[70:71] op_sel_hi:[1,0]
	v_pk_mul_f32 v[66:67], v[66:67], v[70:71] op_sel_hi:[1,0]
	s_andn2_saveexec_b64 s[20:21], s[20:21]
	s_cbranch_execz .LBB0_51

; __device__ __forceinline__ unsigned cvt_pk_bf16(float lo, float hi) { unsigned r; asm volatile("v_cvt_pk_bf16_f32 %0, %1, %2" : "=v"(r) : "v"(lo), "v"(hi)); return r; }
; #define in_mem ARGP(1)
; #define g_mem ARGP(9)
; __global__ void __launch_bounds__(NWAVES * 64, 2) fwd(Args args) {
;     ...
;         for (int m = gw; m < TM; m += NGW) {
;             const f32x4* xr = (const f32x4*)(in_mem + (size_t)m * DM) + F.lane; f32x4 v[16]; float s2 = 0.f;
; #pragma unroll
;             for (int j = 0; j < 16; ++j) { v[j] = xr[64 * j]; s2 += (v[j][0] * v[j][0] + v[j][1] * v[j][1]) + (v[j][2] * v[j][2] + v[j][3] * v[j][3]); }
;             const float rs = 1.0f / sqrtf(wave_sum(s2) * (1.0f / DM) + EPS);
;             u32x2* o8 = (u32x2*)(memn + (size_t)m * DM) + F.lane;
; #pragma unroll
;             for (int j = 0; j < 16; ++j) { const f32x4 g = *((const f32x4*)g_mem + F.lane + 64 * j); u32x2 w; w.x = cvt_pk_bf16(v[j][0] * rs * g[0], v[j][1] * rs * g[1]); w.y = cvt_pk_bf16(v[j][2] * rs * g[2], v[j][3] * rs * g[3]); o8[64 * j] = w; }
.LBB0_77:
	flat_load_dwordx2 v[2:3], v[56:57] offset:8 sc0 sc1
	s_waitcnt vmcnt(0)
	v_add_co_u32_e32 v58, vcc, s3, v52
	s_add_i32 s14, s14, s68
	s_nop 0
	v_addc_co_u32_e32 v59, vcc, -1, v53, vcc
	s_cmpk_gt_i32 s14, 0x3ff
	s_waitcnt lgkmcnt(0)
	v_lshl_add_u64 v[6:7], v[2:3], 0, v[54:55]
	v_add_co_u32_e32 v8, vcc, 0xffffc400, v6
	v_lshl_add_u64 v[54:55], v[54:55], 0, s[8:9]
	s_nop 0
	v_addc_co_u32_e32 v9, vcc, -1, v7, vcc
	v_add_co_u32_e32 v10, vcc, 0xffffc800, v6
	s_nop 1
	v_addc_co_u32_e32 v11, vcc, -1, v7, vcc
	v_add_co_u32_e32 v12, vcc, 0xffffcc00, v6
	flat_load_dwordx4 v[68:71], v[8:9]
	flat_load_dwordx4 v[2:5], v[6:7]
	flat_load_dwordx4 v[72:75], v[10:11]
	v_addc_co_u32_e32 v13, vcc, -1, v7, vcc
	v_add_co_u32_e32 v8, vcc, 0xffffd000, v6
	flat_load_dwordx4 v[76:79], v[12:13]
	s_nop 0
	v_addc_co_u32_e32 v9, vcc, -1, v7, vcc
	v_add_co_u32_e32 v10, vcc, 0xffffd400, v6
	s_waitcnt vmcnt(0) lgkmcnt(0)
	v_mul_f32_e32 v90, v73, v73
	v_addc_co_u32_e32 v11, vcc, -1, v7, vcc
	v_add_co_u32_e32 v12, vcc, 0xffffd800, v6
	flat_load_dwordx4 v[80:83], v[8:9]
	flat_load_dwordx4 v[46:49], v[10:11]
	v_addc_co_u32_e32 v13, vcc, -1, v7, vcc
	v_add_co_u32_e32 v8, vcc, 0xffffdc00, v6
	v_mul_f32_e32 v91, v75, v75
	s_nop 0
	v_addc_co_u32_e32 v9, vcc, -1, v7, vcc
	v_add_co_u32_e32 v10, vcc, 0xffffe000, v6
	flat_load_dwordx4 v[42:45], v[12:13]
	flat_load_dwordx4 v[38:41], v[8:9]
	v_addc_co_u32_e32 v11, vcc, -1, v7, vcc
	v_add_co_u32_e32 v8, vcc, 0xffffe400, v6
	v_fmac_f32_e32 v90, v72, v72
	s_nop 0
	v_addc_co_u32_e32 v9, vcc, -1, v7, vcc
	v_add_co_u32_e32 v12, vcc, 0xffffe800, v6
	flat_load_dwordx4 v[34:37], v[10:11]
	flat_load_dwordx4 v[30:33], v[8:9]
	v_addc_co_u32_e32 v13, vcc, -1, v7, vcc
	v_add_co_u32_e32 v8, vcc, 0xffffec00, v6
	v_fmac_f32_e32 v91, v74, v74
	s_nop 0
	v_addc_co_u32_e32 v9, vcc, -1, v7, vcc
	v_add_co_u32_e32 v10, vcc, 0xfffff000, v6
	flat_load_dwordx4 v[26:29], v[12:13]
	flat_load_dwordx4 v[22:25], v[8:9]
	v_addc_co_u32_e32 v11, vcc, -1, v7, vcc
	v_add_co_u32_e32 v8, vcc, 0xfffff400, v6
	v_mul_f32_e32 v92, v79, v79
	s_nop 0
	v_addc_co_u32_e32 v9, vcc, -1, v7, vcc
	v_add_co_u32_e32 v84, vcc, 0xfffff800, v6
	flat_load_dwordx4 v[18:21], v[10:11]
	flat_load_dwordx4 v[14:17], v[8:9]
	v_addc_co_u32_e32 v85, vcc, -1, v7, vcc
	v_add_co_u32_e32 v86, vcc, 0xfffffc00, v6
	v_fmac_f32_e32 v92, v78, v78
	s_nop 0
	v_addc_co_u32_e32 v87, vcc, -1, v7, vcc
	flat_load_dwordx4 v[10:13], v[84:85]
	flat_load_dwordx4 v[6:9], v[86:87]
	flat_load_dwordx2 v[88:89], v[56:57] offset:72 sc0 sc1
	s_waitcnt vmcnt(0)
	v_mul_f32_e32 v84, v69, v69
	v_mul_f32_e32 v85, v71, v71
	v_mul_f32_e32 v86, v3, v3
	v_mul_f32_e32 v87, v5, v5
	v_fmac_f32_e32 v84, v68, v68
	v_fmac_f32_e32 v85, v70, v70
	v_fmac_f32_e32 v86, v2, v2
	v_fmac_f32_e32 v87, v4, v4
	v_add_f32_e32 v84, v84, v85
	v_mul_f32_e32 v85, v77, v77
	v_add_f32_e32 v93, v86, v87
	v_add_f32_e32 v86, v90, v91
	v_fmac_f32_e32 v85, v76, v76
	v_add_f32_e32 v84, v84, v86
	v_add_f32_e32 v85, v85, v92
	v_add_f32_e32 v84, v84, v85
	s_waitcnt lgkmcnt(0)
	v_mul_f32_e32 v87, v81, v81
	v_mul_f32_e32 v90, v83, v83
	v_fmac_f32_e32 v87, v80, v80
	v_fmac_f32_e32 v90, v82, v82
	v_mul_f32_e32 v86, v47, v47
	v_mul_f32_e32 v91, v49, v49
	v_add_f32_e32 v85, v87, v90
	v_fmac_f32_e32 v86, v46, v46
	v_fmac_f32_e32 v91, v48, v48
	v_add_f32_e32 v84, v84, v85
	v_mul_f32_e32 v87, v43, v43
	v_mul_f32_e32 v90, v45, v45
	v_add_f32_e32 v85, v86, v91
	v_fmac_f32_e32 v87, v42, v42
	v_fmac_f32_e32 v90, v44, v44
	v_mul_f32_e32 v86, v39, v39
	v_mul_f32_e32 v91, v41, v41
	v_add_f32_e32 v84, v84, v85
	v_add_f32_e32 v85, v87, v90
	v_fmac_f32_e32 v86, v38, v38
	v_fmac_f32_e32 v91, v40, v40
	v_mul_f32_e32 v87, v35, v35
	v_mul_f32_e32 v90, v37, v37
	v_add_f32_e32 v84, v84, v85
	v_add_f32_e32 v85, v86, v91
	v_fmac_f32_e32 v87, v34, v34
	v_fmac_f32_e32 v90, v36, v36
	v_mul_f32_e32 v86, v31, v31
	v_mul_f32_e32 v91, v33, v33
	v_add_f32_e32 v84, v84, v85
	v_add_f32_e32 v85, v87, v90
	v_fmac_f32_e32 v86, v30, v30
	v_fmac_f32_e32 v91, v32, v32
	v_mul_f32_e32 v87, v27, v27
	v_mul_f32_e32 v90, v29, v29
	v_add_f32_e32 v84, v84, v85
	v_add_f32_e32 v85, v86, v91
	v_fmac_f32_e32 v87, v26, v26
	v_fmac_f32_e32 v90, v28, v28
	v_mul_f32_e32 v86, v23, v23
	v_mul_f32_e32 v91, v25, v25
	v_add_f32_e32 v84, v84, v85
	v_add_f32_e32 v85, v87, v90
	v_fmac_f32_e32 v86, v22, v22
	v_fmac_f32_e32 v91, v24, v24
	v_mul_f32_e32 v87, v19, v19
	v_mul_f32_e32 v90, v21, v21
	v_add_f32_e32 v84, v84, v85
	v_add_f32_e32 v85, v86, v91
	v_fmac_f32_e32 v87, v18, v18
	v_fmac_f32_e32 v90, v20, v20
	v_mul_f32_e32 v86, v15, v15
	v_mul_f32_e32 v91, v17, v17
	v_add_f32_e32 v84, v84, v85
	v_add_f32_e32 v85, v87, v90
	v_fmac_f32_e32 v86, v14, v14
	v_fmac_f32_e32 v91, v16, v16
	v_mul_f32_e32 v87, v11, v11
	v_mul_f32_e32 v90, v13, v13
	v_add_f32_e32 v92, v84, v85
	v_add_f32_e32 v86, v86, v91
	v_fmac_f32_e32 v87, v10, v10
	v_fmac_f32_e32 v90, v12, v12
	v_lshl_add_u64 v[84:85], v[88:89], 0, v[50:51]
	v_lshl_add_u64 v[180:181], v[88:89], 0, v[50:51]
	v_add_f32_e32 v88, v92, v86
	v_add_f32_e32 v89, v87, v90
	flat_load_dwordx4 v[84:87], v[84:85]
	v_add_co_u32_e32 v176, vcc, s11, v180
	s_nop 1
	v_addc_co_u32_e32 v177, vcc, 0, v181, vcc
	v_add_co_u32_e32 v174, vcc, s12, v180
	s_nop 1
	v_addc_co_u32_e32 v175, vcc, 0, v181, vcc
	v_add_co_u32_e32 v172, vcc, s13, v180
	s_nop 1
	v_addc_co_u32_e32 v173, vcc, 0, v181, vcc
	global_load_dwordx4 v[184:187], v[180:181], off offset:1024
	global_load_dwordx4 v[188:191], v[180:181], off offset:2048
	global_load_dwordx4 v[192:195], v[180:181], off offset:3072
	global_load_dwordx4 v[196:199], v[176:177], off
	global_load_dwordx4 v[200:203], v[176:177], off offset:1024
	global_load_dwordx4 v[204:207], v[176:177], off offset:2048
	global_load_dwordx4 v[208:211], v[176:177], off offset:3072
	global_load_dwordx4 v[212:215], v[174:175], off
	global_load_dwordx4 v[216:219], v[174:175], off offset:1024
	global_load_dwordx4 v[220:223], v[174:175], off offset:2048
	global_load_dwordx4 v[224:227], v[174:175], off offset:3072
	global_load_dwordx4 v[228:231], v[172:173], off
	global_load_dwordx4 v[232:235], v[172:173], off offset:1024
	global_load_dwordx4 v[236:239], v[172:173], off offset:2048
	global_load_dwordx4 v[240:243], v[172:173], off offset:3072
	v_mul_f32_e32 v91, v7, v7
	v_mul_f32_e32 v94, v9, v9
	v_fmac_f32_e32 v91, v6, v6
	v_fmac_f32_e32 v94, v8, v8
	v_add_f32_e32 v88, v88, v89
	v_add_f32_e32 v89, v91, v94
	v_add_f32_e32 v88, v88, v89
	v_add_f32_e32 v88, v88, v93
	s_nop 1
	v_mov_b32_dpp v89, v88 quad_perm:[1,0,3,2] row_mask:0xf bank_mask:0xf
	s_waitcnt lgkmcnt(0)
; __device__ __forceinline__ unsigned cvt_pk_bf16(float lo, float hi) { unsigned r; asm volatile("v_cvt_pk_bf16_f32 %0, %1, %2" : "=v"(r) : "v"(lo), "v"(hi)); return r; }
; #define g_mem ARGP(9)
; __device__ __forceinline__ float wave_sum(float v) {
; #pragma unroll
;     for (int o = 1; o < 64; o <<= 1) v += __shfl_xor(v, o);
;     return v;
; }
; __global__ void __launch_bounds__(NWAVES * 64, 2) fwd(Args args) {
;     ...
;             const float rs = 1.0f / sqrtf(wave_sum(s2) * (1.0f / DM) + EPS);
;             u32x2* o8 = (u32x2*)(memn + (size_t)m * DM) + F.lane;
; #pragma unroll
;             for (int j = 0; j < 16; ++j) { const f32x4 g = *((const f32x4*)g_mem + F.lane + 64 * j); u32x2 w; w.x = cvt_pk_bf16(v[j][0] * rs * g[0], v[j][1] * rs * g[1]); w.y = cvt_pk_bf16(v[j][2] * rs * g[2], v[j][3] * rs * g[3]); o8[64 * j] = w; }
	v_add_f32_e32 v88, v88, v89
	s_nop 1
	v_mov_b32_dpp v89, v88 quad_perm:[2,3,0,1] row_mask:0xf bank_mask:0xf
	s_waitcnt lgkmcnt(0)
	v_add_f32_e32 v88, v88, v89
	s_nop 1
	v_mov_b32_dpp v89, v88 row_half_mirror row_mask:0xf bank_mask:0xf
	s_waitcnt lgkmcnt(0)
	v_add_f32_e32 v88, v88, v89
	s_nop 1
	v_mov_b32_dpp v89, v88 row_mirror row_mask:0xf bank_mask:0xf
	s_waitcnt lgkmcnt(0)
	v_add_f32_e32 v88, v88, v89
	s_waitcnt lgkmcnt(0)
	v_mov_b32_e32 v89, v88
	s_nop 1
	v_permlane16_swap_b32_e32 v88, v89
	s_nop 0
	v_add_f32_e32 v88, v88, v89
	s_waitcnt lgkmcnt(0)
	v_mov_b32_e32 v89, v88
	s_nop 1
	v_permlane32_swap_b32_e32 v88, v89
	s_nop 0
	v_add_f32_e32 v88, v88, v89
	v_fmamk_f32 v88, v88, 0x39800000, v66
	v_mul_f32_e32 v89, 0x4f800000, v88
	v_cmp_gt_f32_e32 vcc, s10, v88
	s_nop 1
	v_cndmask_b32_e32 v88, v88, v89, vcc
	v_sqrt_f32_e32 v89, v88
	s_nop 0
	v_add_u32_e32 v90, -1, v89
	v_add_u32_e32 v91, 1, v89
	v_fma_f32 v92, -v90, v89, v88
	v_fma_f32 v93, -v91, v89, v88
	v_cmp_ge_f32_e64 s[4:5], 0, v92
	s_nop 1
	v_cndmask_b32_e64 v89, v89, v90, s[4:5]
	v_cmp_lt_f32_e64 s[4:5], 0, v93
	s_nop 1
	v_cndmask_b32_e64 v89, v89, v91, s[4:5]
	v_mul_f32_e32 v90, 0x37800000, v89
	v_cndmask_b32_e32 v89, v89, v90, vcc
	v_cmp_class_f32_e32 vcc, v88, v67
	s_nop 1
	v_cndmask_b32_e32 v88, v89, v88, vcc
	v_div_scale_f32 v89, s[4:5], v88, v88, 1.0
	v_rcp_f32_e32 v91, v89
	v_div_scale_f32 v90, vcc, 1.0, v88, 1.0
	v_fma_f32 v92, -v89, v91, 1.0
	v_fmac_f32_e32 v91, v92, v91
	v_mul_f32_e32 v92, v90, v91
	v_fma_f32 v93, -v89, v92, v90
	v_fmac_f32_e32 v92, v93, v91
	v_fma_f32 v89, -v89, v92, v90
	v_div_fmas_f32 v89, v89, v91, v92
	v_div_fixup_f32 v88, v89, v88, 1.0
	v_mul_f32_e32 v68, v88, v68
	v_mul_f32_e32 v69, v88, v69
	v_mul_f32_e32 v70, v88, v70
	v_mul_f32_e32 v71, v88, v71
	v_mul_f32_e32 v89, v88, v46
	v_mul_f32_e32 v90, v88, v47
	s_waitcnt vmcnt(0)
	v_mul_f32_e32 v46, v84, v68
	v_mul_f32_e32 v47, v85, v69
	v_mul_f32_e32 v91, v88, v48
	v_mul_f32_e32 v92, v88, v49
	v_mul_f32_e32 v48, v86, v70
	v_mul_f32_e32 v49, v87, v71
	v_cvt_pk_bf16_f32 v46, v46, v47
	v_cvt_pk_bf16_f32 v47, v48, v49
	global_store_dwordx2 v[58:59], v[46:47], off offset:-3584
	v_mul_f32_e32 v72, v88, v72
	v_mul_f32_e32 v73, v88, v73
	v_mul_f32_e32 v74, v88, v74
	v_mul_f32_e32 v75, v88, v75
	v_mul_f32_e32 v76, v88, v76
	v_mul_f32_e32 v77, v88, v77
	v_mul_f32_e32 v78, v88, v78
	v_mul_f32_e32 v79, v88, v79
	v_mul_f32_e32 v80, v88, v80
	v_mul_f32_e32 v81, v88, v81
	v_mul_f32_e32 v82, v88, v82
	v_mul_f32_e32 v83, v88, v83
	v_mul_f32_e32 v42, v88, v42
	v_mul_f32_e32 v43, v88, v43
	v_mul_f32_e32 v44, v88, v44
	v_mul_f32_e32 v45, v88, v45
	v_mul_f32_e32 v38, v88, v38
	v_mul_f32_e32 v39, v88, v39
	v_mul_f32_e32 v40, v88, v40
	v_mul_f32_e32 v41, v88, v41
	v_mul_f32_e32 v34, v88, v34
	v_mul_f32_e32 v35, v88, v35
	v_mul_f32_e32 v36, v88, v36
	v_mul_f32_e32 v37, v88, v37
	v_mul_f32_e32 v30, v88, v30
	v_mul_f32_e32 v31, v88, v31
	v_mul_f32_e32 v32, v88, v32
	v_mul_f32_e32 v33, v88, v33
	v_mul_f32_e32 v26, v88, v26
	v_mul_f32_e32 v27, v88, v27
	v_mul_f32_e32 v28, v88, v28
	v_mul_f32_e32 v29, v88, v29
	v_mul_f32_e32 v22, v88, v22
	v_mul_f32_e32 v23, v88, v23
	v_mul_f32_e32 v24, v88, v24
	v_mul_f32_e32 v25, v88, v25
	v_mul_f32_e32 v18, v88, v18
	v_mul_f32_e32 v19, v88, v19
	v_mul_f32_e32 v20, v88, v20
	v_mul_f32_e32 v21, v88, v21
	v_mul_f32_e32 v14, v88, v14
	v_mul_f32_e32 v15, v88, v15
	v_mul_f32_e32 v16, v88, v16
	v_mul_f32_e32 v17, v88, v17
	v_mul_f32_e32 v10, v88, v10
	v_mul_f32_e32 v11, v88, v11
	v_mul_f32_e32 v12, v88, v12
	v_mul_f32_e32 v13, v88, v13
	v_mul_f32_e32 v6, v88, v6
	v_mul_f32_e32 v7, v88, v7
	v_mul_f32_e32 v8, v88, v8
	v_mul_f32_e32 v9, v88, v9
	v_mul_f32_e32 v2, v88, v2
	v_mul_f32_e32 v3, v88, v3
	v_mul_f32_e32 v4, v88, v4
	v_mul_f32_e32 v5, v88, v5
	v_lshl_add_u64 v[46:47], v[46:47], 0, v[50:51]
	s_nop 1
	v_mov_b32_e32 v46, v184
	v_mov_b32_e32 v47, v185
	v_mov_b32_e32 v48, v186
	v_mov_b32_e32 v49, v187
	v_mul_f32_e32 v46, v46, v72
	v_mul_f32_e32 v47, v47, v73
	v_mul_f32_e32 v48, v48, v74
	v_mul_f32_e32 v49, v49, v75
	v_cvt_pk_bf16_f32 v46, v46, v47
	v_cvt_pk_bf16_f32 v47, v48, v49
	global_store_dwordx2 v[58:59], v[46:47], off offset:-3072
	v_lshl_add_u64 v[46:47], v[46:47], 0, v[50:51]
	s_nop 1
	v_mov_b32_e32 v46, v188
	v_mov_b32_e32 v47, v189
	v_mov_b32_e32 v48, v190
	v_mov_b32_e32 v49, v191
	v_mul_f32_e32 v46, v46, v76
	v_mul_f32_e32 v47, v47, v77
	v_mul_f32_e32 v48, v48, v78
	v_mul_f32_e32 v49, v49, v79
	v_cvt_pk_bf16_f32 v46, v46, v47
	v_cvt_pk_bf16_f32 v47, v48, v49
	global_store_dwordx2 v[58:59], v[46:47], off offset:-2560
	v_lshl_add_u64 v[46:47], v[46:47], 0, v[50:51]
	s_nop 1
	v_mov_b32_e32 v46, v192
	v_mov_b32_e32 v47, v193
	v_mov_b32_e32 v48, v194
	v_mov_b32_e32 v49, v195
	v_mul_f32_e32 v46, v46, v80
	v_mul_f32_e32 v47, v47, v81
	v_mul_f32_e32 v48, v48, v82
	v_mul_f32_e32 v49, v49, v83
	v_cvt_pk_bf16_f32 v46, v46, v47
	v_cvt_pk_bf16_f32 v47, v48, v49
	global_store_dwordx2 v[58:59], v[46:47], off offset:-2048
; __device__ __forceinline__ unsigned cvt_pk_bf16(float lo, float hi) { unsigned r; asm volatile("v_cvt_pk_bf16_f32 %0, %1, %2" : "=v"(r) : "v"(lo), "v"(hi)); return r; }
; #define g_mem ARGP(9)
; __global__ void __launch_bounds__(NWAVES * 64, 2) fwd(Args args) {
;     ...
;             u32x2* o8 = (u32x2*)(memn + (size_t)m * DM) + F.lane;
; #pragma unroll
;             for (int j = 0; j < 16; ++j) { const f32x4 g = *((const f32x4*)g_mem + F.lane + 64 * j); u32x2 w; w.x = cvt_pk_bf16(v[j][0] * rs * g[0], v[j][1] * rs * g[1]); w.y = cvt_pk_bf16(v[j][2] * rs * g[2], v[j][3] * rs * g[3]); o8[64 * j] = w; }
	v_lshl_add_u64 v[46:47], v[46:47], 0, v[50:51]
	s_nop 1
	s_nop 1
	v_mov_b32_e32 v46, v196
	v_mov_b32_e32 v47, v197
	v_mov_b32_e32 v48, v198
	v_mov_b32_e32 v49, v199
	v_mul_f32_e32 v46, v46, v89
	v_mul_f32_e32 v47, v47, v90
	v_mul_f32_e32 v48, v48, v91
	v_mul_f32_e32 v49, v49, v92
	v_cvt_pk_bf16_f32 v46, v46, v47
	v_cvt_pk_bf16_f32 v47, v48, v49
	global_store_dwordx2 v[58:59], v[46:47], off offset:-1536
	v_lshl_add_u64 v[46:47], v[46:47], 0, v[50:51]
	s_nop 1
	s_nop 1
	v_mov_b32_e32 v46, v200
	v_mov_b32_e32 v47, v201
	v_mov_b32_e32 v48, v202
	v_mov_b32_e32 v49, v203
	v_mul_f32_e32 v42, v46, v42
	v_mul_f32_e32 v43, v47, v43
	v_mul_f32_e32 v44, v48, v44
	v_mul_f32_e32 v45, v49, v45
	v_cvt_pk_bf16_f32 v42, v42, v43
	v_cvt_pk_bf16_f32 v43, v44, v45
	global_store_dwordx2 v[58:59], v[42:43], off offset:-1024
	v_lshl_add_u64 v[42:43], v[42:43], 0, v[50:51]
	s_nop 1
	s_nop 1
	v_mov_b32_e32 v42, v204
	v_mov_b32_e32 v43, v205
	v_mov_b32_e32 v44, v206
	v_mov_b32_e32 v45, v207
	v_mul_f32_e32 v38, v42, v38
	v_mul_f32_e32 v39, v43, v39
	v_mul_f32_e32 v40, v44, v40
	v_mul_f32_e32 v41, v45, v41
	v_cvt_pk_bf16_f32 v38, v38, v39
	v_cvt_pk_bf16_f32 v39, v40, v41
	global_store_dwordx2 v[58:59], v[38:39], off offset:-512
	v_lshl_add_u64 v[38:39], v[38:39], 0, v[50:51]
	s_nop 1
	s_nop 1
	v_mov_b32_e32 v38, v208
	v_mov_b32_e32 v39, v209
	v_mov_b32_e32 v40, v210
	v_mov_b32_e32 v41, v211
	v_mul_f32_e32 v34, v38, v34
	v_mul_f32_e32 v35, v39, v35
	v_mul_f32_e32 v36, v40, v36
	v_mul_f32_e32 v37, v41, v37
	v_cvt_pk_bf16_f32 v34, v34, v35
	v_cvt_pk_bf16_f32 v35, v36, v37
	global_store_dwordx2 v[52:53], v[34:35], off offset:-4096
	v_lshl_add_u64 v[34:35], v[34:35], 0, v[50:51]
	s_nop 1
	s_nop 1
	v_mov_b32_e32 v34, v212
	v_mov_b32_e32 v35, v213
	v_mov_b32_e32 v36, v214
	v_mov_b32_e32 v37, v215
	v_mul_f32_e32 v30, v34, v30
	v_mul_f32_e32 v31, v35, v31
	v_mul_f32_e32 v32, v36, v32
	v_mul_f32_e32 v33, v37, v33
	v_cvt_pk_bf16_f32 v30, v30, v31
	v_cvt_pk_bf16_f32 v31, v32, v33
	global_store_dwordx2 v[52:53], v[30:31], off offset:-3584
	v_lshl_add_u64 v[30:31], v[30:31], 0, v[50:51]
	s_nop 1
	s_nop 1
	v_mov_b32_e32 v30, v216
	v_mov_b32_e32 v31, v217
	v_mov_b32_e32 v32, v218
	v_mov_b32_e32 v33, v219
	v_mul_f32_e32 v26, v30, v26
	v_mul_f32_e32 v27, v31, v27
	v_mul_f32_e32 v28, v32, v28
	v_mul_f32_e32 v29, v33, v29
	v_cvt_pk_bf16_f32 v26, v26, v27
	v_cvt_pk_bf16_f32 v27, v28, v29
	global_store_dwordx2 v[52:53], v[26:27], off offset:-3072
	v_lshl_add_u64 v[26:27], v[26:27], 0, v[50:51]
	s_nop 1
	s_nop 1
	v_mov_b32_e32 v26, v220
	v_mov_b32_e32 v27, v221
	v_mov_b32_e32 v28, v222
	v_mov_b32_e32 v29, v223
	v_mul_f32_e32 v22, v26, v22
	v_mul_f32_e32 v23, v27, v23
	v_mul_f32_e32 v24, v28, v24
	v_mul_f32_e32 v25, v29, v25
	v_cvt_pk_bf16_f32 v22, v22, v23
	v_cvt_pk_bf16_f32 v23, v24, v25
	global_store_dwordx2 v[52:53], v[22:23], off offset:-2560
	v_lshl_add_u64 v[22:23], v[22:23], 0, v[50:51]
	s_nop 1
	s_nop 1
	v_mov_b32_e32 v22, v224
	v_mov_b32_e32 v23, v225
	v_mov_b32_e32 v24, v226
	v_mov_b32_e32 v25, v227
	v_mul_f32_e32 v18, v22, v18
	v_mul_f32_e32 v19, v23, v19
	v_mul_f32_e32 v20, v24, v20
	v_mul_f32_e32 v21, v25, v21
	v_cvt_pk_bf16_f32 v18, v18, v19
	v_cvt_pk_bf16_f32 v19, v20, v21
	global_store_dwordx2 v[52:53], v[18:19], off offset:-2048
	v_lshl_add_u64 v[18:19], v[18:19], 0, v[50:51]
	s_nop 1
	s_nop 1
	v_mov_b32_e32 v18, v228
	v_mov_b32_e32 v19, v229
	v_mov_b32_e32 v20, v230
	v_mov_b32_e32 v21, v231
	v_mul_f32_e32 v14, v18, v14
	v_mul_f32_e32 v15, v19, v15
	v_mul_f32_e32 v16, v20, v16
	v_mul_f32_e32 v17, v21, v17
	v_cvt_pk_bf16_f32 v14, v14, v15
	v_cvt_pk_bf16_f32 v15, v16, v17
	global_store_dwordx2 v[52:53], v[14:15], off offset:-1536
	v_lshl_add_u64 v[14:15], v[14:15], 0, v[50:51]
	s_nop 1
	s_nop 1
	v_mov_b32_e32 v14, v232
	v_mov_b32_e32 v15, v233
	v_mov_b32_e32 v16, v234
	v_mov_b32_e32 v17, v235
	v_mul_f32_e32 v10, v14, v10
	v_mul_f32_e32 v11, v15, v11
	v_mul_f32_e32 v12, v16, v12
	v_mul_f32_e32 v13, v17, v13
	v_cvt_pk_bf16_f32 v10, v10, v11
	v_cvt_pk_bf16_f32 v11, v12, v13
	global_store_dwordx2 v[52:53], v[10:11], off offset:-1024
	v_lshl_add_u64 v[10:11], v[10:11], 0, v[50:51]
	s_nop 1
	s_nop 1
	v_mov_b32_e32 v10, v236
	v_mov_b32_e32 v11, v237
	v_mov_b32_e32 v12, v238
	v_mov_b32_e32 v13, v239
	v_mul_f32_e32 v6, v10, v6
	v_mul_f32_e32 v7, v11, v7
	v_mul_f32_e32 v8, v12, v8
	v_mul_f32_e32 v9, v13, v9
	v_cvt_pk_bf16_f32 v6, v6, v7
	v_cvt_pk_bf16_f32 v7, v8, v9
	global_store_dwordx2 v[52:53], v[6:7], off offset:-512
	v_lshl_add_u64 v[6:7], v[6:7], 0, v[50:51]
	s_nop 1
	s_nop 1
	v_mov_b32_e32 v6, v240
	v_mov_b32_e32 v7, v241
	v_mov_b32_e32 v8, v242
	v_mov_b32_e32 v9, v243
	v_mul_f32_e32 v2, v6, v2
	v_mul_f32_e32 v3, v7, v3
	v_mul_f32_e32 v4, v8, v4
	v_mul_f32_e32 v5, v9, v5
	v_cvt_pk_bf16_f32 v2, v2, v3
	v_cvt_pk_bf16_f32 v3, v4, v5
	global_store_dwordx2 v[52:53], v[2:3], off
	v_lshl_add_u64 v[52:53], v[52:53], 0, s[6:7]
	s_cbranch_scc0 .LBB0_77

; __device__ __forceinline__ void p0_load(const P0Item& it, f32x4 (&w)[16], int lane) {
;     const unsigned voff = (unsigned)(((lane >> 4) * it.ldw + (lane & 15) * 4) * 4);
; #pragma unroll
;     for (int i = 0; i < 16; ++i) w[i] = __builtin_nontemporal_load((const f32x4*)((const char*)(it.src + (size_t)(4 * i) * it.ldw) + voff));
; __global__ void __launch_bounds__(NWAVES * 64, 2) fwd(Args args) {
;     ...
;     if (IN(2)) {
;         const int slot = ((int)blockIdx.x & 63) % 3;
.LBB0_144:
	s_add_u32 s0, s78, 0x46000000
	s_addc_u32 s1, s79, 0
	v_writelane_b32 v254, s46, 8
	s_add_u32 s16, s78, 0x300000
	v_writelane_b32 v254, s0, 9
	s_addc_u32 s17, s79, 0
	s_nop 0
	v_writelane_b32 v254, s1, 10
	s_add_u32 s0, s78, 0x6800000
	v_writelane_b32 v254, s0, 11
	s_addc_u32 s0, s79, 0
	s_add_u32 s58, s78, 0x8800000
	s_addc_u32 s59, s79, 0
	s_add_u32 s14, s78, 0xc800000
	s_addc_u32 s15, s79, 0
	s_add_u32 s3, s78, 0xe800000
	s_addc_u32 s56, s79, 0
	v_writelane_b32 v254, s0, 12
	s_add_u32 s0, s78, 0x18800000
	s_addc_u32 s1, s79, 0
	s_add_u32 s74, s78, 0x26000000
	s_addc_u32 s75, s79, 0
	s_add_u32 s90, s78, 0x2e000000
	s_addc_u32 s91, s79, 0
	s_add_u32 s83, s78, 0x3a000000
	s_addc_u32 s95, s79, 0
	v_writelane_b32 v254, s0, 13
	s_cmp_lt_i32 s96, 3
	s_nop 0
	v_writelane_b32 v254, s1, 14
	s_cselect_b64 s[0:1], -1, 0
	s_cmp_gt_i32 s97, 2
	s_cselect_b64 s[4:5], -1, 0
	s_and_b64 s[18:19], s[0:1], s[4:5]
	s_mov_b32 s0, s68
	v_writelane_b32 v254, s0, 15
	s_andn2_b64 vcc, exec, s[18:19]
	s_nop 0
	v_writelane_b32 v254, s1, 16
	v_writelane_b32 v254, s72, 17
	s_nop 1
	v_writelane_b32 v254, s73, 18
	v_writelane_b32 v254, s74, 19
	s_nop 1
	v_writelane_b32 v254, s75, 20
	s_cbranch_vccnz .LBB0_533
	s_add_u32 s20, s78, 0x100000
	s_addc_u32 s21, s79, 0
	s_add_u32 s33, s78, 0x10800000
	s_addc_u32 s60, s79, 0
	s_and_b32 s0, s2, 63
	s_mul_i32 s1, s0, 0x56
	s_lshr_b32 s1, s1, 8
	s_mul_i32 s1, s1, 3
	s_sub_i32 s0, s0, s1
	s_and_b32 s61, s0, 0xff
	s_cmp_lg_u32 s61, 0
	s_mov_b32 s26, 0
	s_cbranch_scc1 .LBB0_223
	v_mov_b32_e32 v134, v182
	v_readlane_b32 s24, v254, 8
	s_mov_b32 s25, s2
	v_mov_b64_e32 v[2:3], s[92:93]
	flat_load_dwordx2 v[138:139], v[2:3] offset:120 sc0 sc1
	s_lshl_b32 s0, s24, 8
	s_add_i32 s10, s0, s25
	s_ashr_i32 s0, s10, 31
	s_lshr_b32 s0, s0, 24
	s_add_i32 s0, s10, s0
	s_ashr_i32 s1, s0, 8
	s_and_b32 s0, s0, 0x3ffff00
	s_sub_i32 s4, s10, s0
	s_lshl_b32 s0, s1, 6
	s_ashr_i32 s1, s0, 31
	flat_load_dwordx2 v[142:143], v[2:3] offset:112 sc0 sc1
	s_waitcnt vmcnt(0)
	v_lshlrev_b32_e32 v2, 4, v134
	s_lshl_b32 s8, s4, 6
	s_lshl_b64 s[4:5], s[0:1], 16
	v_ashrrev_i32_e32 v150, 4, v134
	v_and_b32_e32 v155, 0xf0, v2
	s_ashr_i32 s9, s8, 31
	v_mov_b32_e32 v141, 0
	v_lshl_or_b32 v140, v150, 16, v155
	s_mov_b32 s27, 0x40000
	s_mov_b32 s28, 0x80000
	s_mov_b32 s29, 0xc0000
	s_mov_b32 s30, 0x100000
	s_mov_b32 s31, 0x140000
	s_mov_b32 s34, 0x180000
	s_mov_b32 s35, 0x1c0000
	s_mov_b32 s36, 0x200000
	s_mov_b32 s37, 0x240000
	s_mov_b32 s38, 0x280000
	s_mov_b32 s39, 0x2c0000
	s_mov_b32 s40, 0x300000
	v_ashrrev_i32_e32 v152, 3, v134
	v_lshlrev_b32_e32 v136, 2, v150
	v_mov_b32_e32 v137, v141
	v_mov_b32_e32 v145, v141
	s_mov_b32 s42, 0x10000
	s_mov_b32 s43, 0x20000
	s_mov_b32 s44, 0x30000
	s_mov_b32 s45, 0x50000
	s_mov_b32 s46, 0x60000
	s_waitcnt lgkmcnt(0)
	v_lshl_add_u64 v[2:3], v[138:139], 0, s[4:5]
	v_lshl_add_u64 v[2:3], s[8:9], 2, v[2:3]
	v_lshl_add_u64 v[58:59], v[2:3], 0, v[140:141]
	v_add_co_u32_e32 v6, vcc, s27, v58
	s_mov_b32 s4, 0x340000
	s_nop 0
	v_addc_co_u32_e32 v7, vcc, 0, v59, vcc
	v_add_co_u32_e32 v10, vcc, s28, v58
	s_lshl_b64 s[8:9], s[8:9], 13
	s_nop 0
	v_addc_co_u32_e32 v11, vcc, 0, v59, vcc
	v_add_co_u32_e32 v14, vcc, s29, v58
	v_lshl_add_u64 v[66:67], s[0:1], 2, v[142:143]
	s_nop 0
	v_addc_co_u32_e32 v15, vcc, 0, v59, vcc
	v_add_co_u32_e32 v18, vcc, s30, v58
	v_cmp_eq_u64_e64 s[6:7], 0, v[142:143]
	s_nop 0
	v_addc_co_u32_e32 v19, vcc, 0, v59, vcc
	v_add_co_u32_e32 v22, vcc, s31, v58
	v_cndmask_b32_e64 v148, v66, 0, s[6:7]
	s_nop 0
	v_addc_co_u32_e32 v23, vcc, 0, v59, vcc
	v_add_co_u32_e32 v26, vcc, s34, v58
	v_cndmask_b32_e64 v149, v67, 0, s[6:7]
	s_nop 0
	v_addc_co_u32_e32 v27, vcc, 0, v59, vcc
	v_add_co_u32_e32 v30, vcc, s35, v58
	v_lshlrev_b32_e32 v67, 2, v152
	s_nop 0
	v_addc_co_u32_e32 v31, vcc, 0, v59, vcc
	v_add_co_u32_e32 v34, vcc, s36, v58
	v_lshl_add_u64 v[146:147], v[142:143], 0, v[136:137]
	s_nop 0
	v_addc_co_u32_e32 v35, vcc, 0, v59, vcc
	v_add_co_u32_e32 v38, vcc, s37, v58
	s_nop 1
	v_addc_co_u32_e32 v39, vcc, 0, v59, vcc
	v_add_co_u32_e32 v42, vcc, s38, v58
	flat_load_dwordx4 v[2:5], v[58:59] nt
	s_nop 0
	flat_load_dwordx4 v[6:9], v[6:7] nt
	s_nop 0
	flat_load_dwordx4 v[10:13], v[10:11] nt
	s_nop 0
	flat_load_dwordx4 v[14:17], v[14:15] nt
	s_nop 0
	flat_load_dwordx4 v[18:21], v[18:19] nt
	s_nop 0
	flat_load_dwordx4 v[22:25], v[22:23] nt
	s_nop 0
	flat_load_dwordx4 v[26:29], v[26:27] nt
	s_nop 0
	flat_load_dwordx4 v[30:33], v[30:31] nt
	s_nop 0
	flat_load_dwordx4 v[34:37], v[34:35] nt
	s_nop 0
	flat_load_dwordx4 v[38:41], v[38:39] nt
	v_addc_co_u32_e32 v43, vcc, 0, v59, vcc
	v_add_co_u32_e32 v46, vcc, s39, v58
	s_nop 1
	v_addc_co_u32_e32 v47, vcc, 0, v59, vcc
	v_add_co_u32_e32 v50, vcc, s40, v58
	flat_load_dwordx4 v[42:45], v[42:43] nt
	s_nop 0
	flat_load_dwordx4 v[46:49], v[46:47] nt
	v_addc_co_u32_e32 v51, vcc, 0, v59, vcc
	v_add_co_u32_e32 v54, vcc, s4, v58
	s_mov_b32 s4, 0x380000
	s_nop 0
	v_addc_co_u32_e32 v55, vcc, 0, v59, vcc
	v_add_co_u32_e32 v60, vcc, s4, v58
	s_mov_b32 s4, 0x3c0000
	s_nop 0
	v_addc_co_u32_e32 v61, vcc, 0, v59, vcc
	v_add_co_u32_e32 v62, vcc, s4, v58
	flat_load_dwordx4 v[50:53], v[50:51] nt
	s_nop 0
	flat_load_dwordx4 v[54:57], v[54:55] nt
	v_addc_co_u32_e32 v63, vcc, 0, v59, vcc
	flat_load_dwordx4 v[58:61], v[60:61] nt
	s_nop 0
	flat_load_dwordx4 v[62:65], v[62:63] nt
	s_mul_i32 s4, s24, 0x4400
	s_add_i32 s11, s4, 0
	s_add_u32 s8, s33, s8
	s_addc_u32 s9, s60, s9
	s_lshl_b64 s[0:1], s[0:1], 1
	s_add_u32 s0, s8, s0
	s_movk_i32 s8, 0x110
	v_mul_lo_u32 v66, v150, s8
	v_add3_u32 v151, s11, v155, v66
	v_mul_u32_u24_e32 v248, 0x770, v150
	v_add_u32_e32 v151, v151, v248
	v_lshlrev_b32_e32 v66, 3, v134
	v_and_b32_e32 v153, 56, v66
	v_lshlrev_b32_e32 v66, 13, v152
	v_lshl_or_b32 v144, v153, 1, v66
	v_mul_u32_u24_e32 v66, 0x110, v153
	v_cmp_ne_u64_e64 s[4:5], 0, v[142:143]
	s_addc_u32 s1, s9, s1
	v_add3_u32 v154, s11, v66, v67
	v_mul_u32_u24_e32 v248, 238, v153
	v_sub_u32_e32 v154, v154, v248
	s_add_i32 s41, s10, 0x1000
	s_branch .LBB0_148

.LBB0_162:
	v_mov_b64_e32 v[2:3], s[92:93]
	flat_load_dwordx2 v[130:131], v[2:3] offset:56 sc0 sc1
	flat_load_dwordx2 v[132:133], v[2:3] offset:88 sc0 sc1
	flat_load_dwordx2 v[138:139], v[2:3] offset:96 sc0 sc1
	flat_load_dwordx2 v[140:141], v[2:3] offset:104 sc0 sc1
	flat_load_dwordx2 v[142:143], v[2:3] offset:128 sc0 sc1
	s_waitcnt vmcnt(0)
	s_lshl_b32 s8, s25, 7
	s_add_i32 s8, s8, s24
	s_cmpk_gt_i32 s8, 0xfff
	s_cbranch_scc0 .LBB0_167
	s_cmpk_gt_u32 s8, 0x1fff
	s_cbranch_scc0 .LBB0_168
	s_cmpk_gt_u32 s8, 0x2fff
	s_cbranch_scc0 .LBB0_169
	s_lshl_b32 s0, s24, 6
	s_and_b32 s6, s0, 0xfc0
	s_cmpk_gt_u32 s8, 0x3fff
	s_mov_b32 s1, 0
	s_cbranch_scc0 .LBB0_170
	s_and_b32 s0, s8, 0x7fffffc0
	s_addk_i32 s0, 0xc000
	s_lshl_b64 s[4:5], s[0:1], 14
	s_waitcnt lgkmcnt(0)
	v_lshl_add_u64 v[2:3], v[142:143], 0, s[4:5]
	s_lshl_b32 s4, s6, 2
	s_mov_b32 s5, s1
	v_lshl_add_u64 v[2:3], v[2:3], 0, s[4:5]
	s_lshl_b32 s4, s6, 15
	v_readlane_b32 s10, v254, 13
	v_readlane_b32 s11, v254, 14
	s_add_u32 s4, s10, s4
	s_addc_u32 s5, s11, 0
	s_lshl_b64 s[0:1], s[0:1], 1
	s_add_u32 s4, s4, s0
	s_addc_u32 s5, s5, s1
	s_mov_b64 s[0:1], 0
	s_branch .LBB0_171

; __device__ __forceinline__ void p0_load(const P0Item& it, f32x4 (&w)[16], int lane) {
;     const unsigned voff = (unsigned)(((lane >> 4) * it.ldw + (lane & 15) * 4) * 4);
; #pragma unroll
;     for (int i = 0; i < 16; ++i) w[i] = __builtin_nontemporal_load((const f32x4*)((const char*)(it.src + (size_t)(4 * i) * it.ldw) + voff));
.LBB0_257:
	s_cmp_lg_u32 s61, 1
	s_cbranch_scc1 .LBB0_335
	v_mov_b32_e32 v134, v182
	v_readlane_b32 s26, v254, 8
	s_mov_b32 s27, s2
	v_mov_b64_e32 v[2:3], s[92:93]
	flat_load_dwordx2 v[138:139], v[2:3] offset:120 sc0 sc1
	s_lshl_b32 s0, s26, 8
	s_add_i32 s12, s0, s27
	s_ashr_i32 s0, s12, 31
	s_lshr_b32 s0, s0, 24
	s_add_i32 s0, s12, s0
	s_ashr_i32 s1, s0, 8
	s_and_b32 s0, s0, 0x3ffff00
	s_sub_i32 s6, s12, s0
	s_lshl_b32 s0, s1, 6
	s_ashr_i32 s1, s0, 31
	flat_load_dwordx2 v[142:143], v[2:3] offset:112 sc0 sc1
	s_waitcnt vmcnt(0)
	v_lshlrev_b32_e32 v2, 4, v134
	s_lshl_b32 s10, s6, 6
	s_lshl_b64 s[6:7], s[0:1], 16
	v_ashrrev_i32_e32 v150, 4, v134
	v_and_b32_e32 v156, 0xf0, v2
	s_ashr_i32 s11, s10, 31
	v_mov_b32_e32 v141, 0
	v_lshl_or_b32 v140, v150, 16, v156
	s_mov_b32 s28, 0x40000
	s_mov_b32 s29, 0x80000
	s_mov_b32 s30, 0xc0000
	s_mov_b32 s31, 0x100000
	s_mov_b32 s34, 0x140000
	s_mov_b32 s35, 0x180000
	s_mov_b32 s36, 0x1c0000
	s_mov_b32 s37, 0x200000
	s_mov_b32 s38, 0x240000
	s_mov_b32 s39, 0x280000
	s_mov_b32 s40, 0x2c0000
	s_mov_b32 s41, 0x300000
	v_ashrrev_i32_e32 v152, 3, v134
	v_lshlrev_b32_e32 v136, 2, v150
	v_mov_b32_e32 v137, v141
	s_mov_b32 s42, 0
	v_mov_b32_e32 v145, v141
	s_mov_b32 s44, 0x10000
	s_mov_b32 s45, 0x20000
	s_mov_b32 s46, 0x30000
	s_mov_b32 s47, 0x50000
	s_mov_b32 s48, 0x60000
	s_waitcnt lgkmcnt(0)
	v_lshl_add_u64 v[2:3], v[138:139], 0, s[6:7]
	v_lshl_add_u64 v[2:3], s[10:11], 2, v[2:3]
	v_lshl_add_u64 v[58:59], v[2:3], 0, v[140:141]
	v_add_co_u32_e32 v6, vcc, s28, v58
	s_mov_b32 s6, 0x340000
	s_nop 0
	v_addc_co_u32_e32 v7, vcc, 0, v59, vcc
	v_add_co_u32_e32 v10, vcc, s29, v58
	s_lshl_b64 s[10:11], s[10:11], 13
	s_nop 0
	v_addc_co_u32_e32 v11, vcc, 0, v59, vcc
	v_add_co_u32_e32 v14, vcc, s30, v58
	v_lshl_add_u64 v[66:67], s[0:1], 2, v[142:143]
	s_nop 0
	v_addc_co_u32_e32 v15, vcc, 0, v59, vcc
	v_add_co_u32_e32 v18, vcc, s31, v58
	v_cmp_eq_u64_e64 s[8:9], 0, v[142:143]
	s_nop 0
	v_addc_co_u32_e32 v19, vcc, 0, v59, vcc
	v_add_co_u32_e32 v22, vcc, s34, v58
	v_cndmask_b32_e64 v148, v66, 0, s[8:9]
	s_nop 0
	v_addc_co_u32_e32 v23, vcc, 0, v59, vcc
	v_add_co_u32_e32 v26, vcc, s35, v58
	v_cndmask_b32_e64 v149, v67, 0, s[8:9]
	s_nop 0
	v_addc_co_u32_e32 v27, vcc, 0, v59, vcc
	v_add_co_u32_e32 v30, vcc, s36, v58
	v_lshlrev_b32_e32 v67, 2, v152
	s_nop 0
	v_addc_co_u32_e32 v31, vcc, 0, v59, vcc
	v_add_co_u32_e32 v34, vcc, s37, v58
	v_lshl_add_u64 v[146:147], v[142:143], 0, v[136:137]
	s_nop 0
	v_addc_co_u32_e32 v35, vcc, 0, v59, vcc
	v_add_co_u32_e32 v38, vcc, s38, v58
	s_nop 1
	v_addc_co_u32_e32 v39, vcc, 0, v59, vcc
	v_add_co_u32_e32 v42, vcc, s39, v58
	flat_load_dwordx4 v[2:5], v[58:59] nt
	s_nop 0
	flat_load_dwordx4 v[6:9], v[6:7] nt
	s_nop 0
	flat_load_dwordx4 v[10:13], v[10:11] nt
	s_nop 0
	flat_load_dwordx4 v[14:17], v[14:15] nt
	s_nop 0
	flat_load_dwordx4 v[18:21], v[18:19] nt
	s_nop 0
	flat_load_dwordx4 v[22:25], v[22:23] nt
	s_nop 0
	flat_load_dwordx4 v[26:29], v[26:27] nt
	s_nop 0
	flat_load_dwordx4 v[30:33], v[30:31] nt
	s_nop 0
	flat_load_dwordx4 v[34:37], v[34:35] nt
	s_nop 0
	flat_load_dwordx4 v[38:41], v[38:39] nt
	v_addc_co_u32_e32 v43, vcc, 0, v59, vcc
	v_add_co_u32_e32 v46, vcc, s40, v58
	s_nop 1
	v_addc_co_u32_e32 v47, vcc, 0, v59, vcc
	v_add_co_u32_e32 v50, vcc, s41, v58
	flat_load_dwordx4 v[42:45], v[42:43] nt
	s_nop 0
	flat_load_dwordx4 v[46:49], v[46:47] nt
	v_addc_co_u32_e32 v51, vcc, 0, v59, vcc
	v_add_co_u32_e32 v54, vcc, s6, v58
	s_mov_b32 s6, 0x380000
	s_nop 0
	v_addc_co_u32_e32 v55, vcc, 0, v59, vcc
	v_add_co_u32_e32 v60, vcc, s6, v58
	s_mov_b32 s6, 0x3c0000
	s_nop 0
	v_addc_co_u32_e32 v61, vcc, 0, v59, vcc
	v_add_co_u32_e32 v62, vcc, s6, v58
	flat_load_dwordx4 v[50:53], v[50:51] nt
	s_nop 0
	flat_load_dwordx4 v[54:57], v[54:55] nt
	v_addc_co_u32_e32 v63, vcc, 0, v59, vcc
	flat_load_dwordx4 v[58:61], v[60:61] nt
	s_nop 0
	flat_load_dwordx4 v[62:65], v[62:63] nt
	s_mul_i32 s6, s26, 0x4400
	s_add_i32 s13, s6, 0
	s_add_u32 s10, s33, s10
	s_addc_u32 s11, s60, s11
	s_lshl_b64 s[0:1], s[0:1], 1
	s_add_u32 s0, s10, s0
	s_movk_i32 s10, 0x110
	v_mul_lo_u32 v66, v150, s10
	v_add3_u32 v151, s13, v156, v66
	v_mul_u32_u24_e32 v248, 0x770, v150
	v_add_u32_e32 v151, v151, v248
	v_lshlrev_b32_e32 v66, 3, v134
	v_and_b32_e32 v154, 56, v66
	v_lshlrev_b32_e32 v66, 13, v152
	v_lshl_or_b32 v144, v154, 1, v66
	v_mul_u32_u24_e32 v66, 0x110, v154
	v_cmp_ne_u64_e64 s[6:7], 0, v[142:143]
	s_addc_u32 s1, s11, s1
	v_add3_u32 v155, s13, v66, v67
	v_mul_u32_u24_e32 v248, 238, v154
	v_sub_u32_e32 v155, v155, v248
	s_add_i32 s43, s12, 0x1000
	s_branch .LBB0_260

.LBB0_274:
	v_mov_b64_e32 v[2:3], s[92:93]
	flat_load_dwordx2 v[130:131], v[2:3] offset:56 sc0 sc1
	flat_load_dwordx2 v[132:133], v[2:3] offset:88 sc0 sc1
	flat_load_dwordx2 v[138:139], v[2:3] offset:96 sc0 sc1
	flat_load_dwordx2 v[140:141], v[2:3] offset:104 sc0 sc1
	flat_load_dwordx2 v[142:143], v[2:3] offset:128 sc0 sc1
	s_waitcnt vmcnt(0)
	s_lshl_b32 s10, s27, 7
	s_add_i32 s10, s10, s26
	s_cmpk_gt_i32 s10, 0xfff
	s_cbranch_scc0 .LBB0_279
	s_cmpk_gt_u32 s10, 0x1fff
	s_cbranch_scc0 .LBB0_280
	s_cmpk_gt_u32 s10, 0x2fff
	s_cbranch_scc0 .LBB0_281
	s_lshl_b32 s0, s26, 6
	s_and_b32 s8, s0, 0xfc0
	s_cmpk_gt_u32 s10, 0x3fff
	s_mov_b32 s1, 0
	s_cbranch_scc0 .LBB0_282
	s_and_b32 s0, s10, 0x7fffffc0
	s_addk_i32 s0, 0xc000
	s_lshl_b64 s[6:7], s[0:1], 14
	s_waitcnt lgkmcnt(0)
	v_lshl_add_u64 v[2:3], v[142:143], 0, s[6:7]
	s_lshl_b32 s6, s8, 2
	s_mov_b32 s7, s1
	v_lshl_add_u64 v[2:3], v[2:3], 0, s[6:7]
	s_lshl_b32 s6, s8, 15
	v_readlane_b32 s12, v254, 13
	v_readlane_b32 s13, v254, 14
	s_add_u32 s6, s12, s6
	s_addc_u32 s7, s13, 0
	s_lshl_b64 s[0:1], s[0:1], 1
	s_add_u32 s6, s6, s0
	s_addc_u32 s7, s7, s1
	s_mov_b64 s[0:1], 0
	s_branch .LBB0_283

; __device__ __forceinline__ void p0_load(const P0Item& it, f32x4 (&w)[16], int lane) {
;     const unsigned voff = (unsigned)(((lane >> 4) * it.ldw + (lane & 15) * 4) * 4);
; #pragma unroll
;     for (int i = 0; i < 16; ++i) w[i] = __builtin_nontemporal_load((const f32x4*)((const char*)(it.src + (size_t)(4 * i) * it.ldw) + voff));
.LBB0_456:
	v_mov_b32_e32 v134, v182
	v_readlane_b32 s24, v254, 8
	s_mov_b32 s25, s2
	v_mov_b64_e32 v[2:3], s[92:93]
	flat_load_dwordx2 v[138:139], v[2:3] offset:120 sc0 sc1
	s_lshl_b32 s0, s24, 8
	s_add_i32 s10, s0, s25
	s_ashr_i32 s0, s10, 31
	s_lshr_b32 s0, s0, 24
	s_add_i32 s0, s10, s0
	s_ashr_i32 s1, s0, 8
	s_and_b32 s0, s0, 0x3ffff00
	s_sub_i32 s4, s10, s0
	s_lshl_b32 s0, s1, 6
	s_ashr_i32 s1, s0, 31
	flat_load_dwordx2 v[142:143], v[2:3] offset:112 sc0 sc1
	s_waitcnt vmcnt(0)
	v_lshlrev_b32_e32 v2, 4, v134
	s_lshl_b32 s8, s4, 6
	s_lshl_b64 s[4:5], s[0:1], 16
	v_ashrrev_i32_e32 v150, 4, v134
	v_and_b32_e32 v155, 0xf0, v2
	s_ashr_i32 s9, s8, 31
	v_mov_b32_e32 v141, 0
	v_lshl_or_b32 v140, v150, 16, v155
	s_mov_b32 s26, 0x40000
	s_mov_b32 s27, 0x80000
	s_mov_b32 s28, 0xc0000
	s_mov_b32 s29, 0x100000
	s_mov_b32 s30, 0x140000
	s_mov_b32 s31, 0x180000
	s_mov_b32 s34, 0x1c0000
	s_mov_b32 s35, 0x200000
	s_mov_b32 s36, 0x240000
	s_mov_b32 s37, 0x280000
	s_mov_b32 s38, 0x2c0000
	s_mov_b32 s39, 0x300000
	v_ashrrev_i32_e32 v152, 3, v134
	v_lshlrev_b32_e32 v136, 2, v150
	v_mov_b32_e32 v137, v141
	s_mov_b32 s40, 0
	v_mov_b32_e32 v145, v141
	s_mov_b32 s42, 0x10000
	s_mov_b32 s43, 0x20000
	s_mov_b32 s44, 0x30000
	s_mov_b32 s45, 0x50000
	s_mov_b32 s46, 0x60000
	s_waitcnt lgkmcnt(0)
	v_lshl_add_u64 v[2:3], v[138:139], 0, s[4:5]
	v_lshl_add_u64 v[2:3], s[8:9], 2, v[2:3]
	v_lshl_add_u64 v[58:59], v[2:3], 0, v[140:141]
	v_add_co_u32_e32 v6, vcc, s26, v58
	s_mov_b32 s4, 0x340000
	s_nop 0
	v_addc_co_u32_e32 v7, vcc, 0, v59, vcc
	v_add_co_u32_e32 v10, vcc, s27, v58
	s_lshl_b64 s[8:9], s[8:9], 13
	s_nop 0
	v_addc_co_u32_e32 v11, vcc, 0, v59, vcc
	v_add_co_u32_e32 v14, vcc, s28, v58
	v_lshl_add_u64 v[66:67], s[0:1], 2, v[142:143]
	s_nop 0
	v_addc_co_u32_e32 v15, vcc, 0, v59, vcc
	v_add_co_u32_e32 v18, vcc, s29, v58
	v_cmp_eq_u64_e64 s[6:7], 0, v[142:143]
	s_nop 0
	v_addc_co_u32_e32 v19, vcc, 0, v59, vcc
	v_add_co_u32_e32 v22, vcc, s30, v58
	v_cndmask_b32_e64 v148, v66, 0, s[6:7]
	s_nop 0
	v_addc_co_u32_e32 v23, vcc, 0, v59, vcc
	v_add_co_u32_e32 v26, vcc, s31, v58
	v_cndmask_b32_e64 v149, v67, 0, s[6:7]
	s_nop 0
	v_addc_co_u32_e32 v27, vcc, 0, v59, vcc
	v_add_co_u32_e32 v30, vcc, s34, v58
	v_lshlrev_b32_e32 v67, 2, v152
	s_nop 0
	v_addc_co_u32_e32 v31, vcc, 0, v59, vcc
	v_add_co_u32_e32 v34, vcc, s35, v58
	v_lshl_add_u64 v[146:147], v[142:143], 0, v[136:137]
	s_nop 0
	v_addc_co_u32_e32 v35, vcc, 0, v59, vcc
	v_add_co_u32_e32 v38, vcc, s36, v58
	s_nop 1
	v_addc_co_u32_e32 v39, vcc, 0, v59, vcc
	v_add_co_u32_e32 v42, vcc, s37, v58
	flat_load_dwordx4 v[2:5], v[58:59] nt
	s_nop 0
	flat_load_dwordx4 v[6:9], v[6:7] nt
	s_nop 0
	flat_load_dwordx4 v[10:13], v[10:11] nt
	s_nop 0
	flat_load_dwordx4 v[14:17], v[14:15] nt
	s_nop 0
	flat_load_dwordx4 v[18:21], v[18:19] nt
	s_nop 0
	flat_load_dwordx4 v[22:25], v[22:23] nt
	s_nop 0
	flat_load_dwordx4 v[26:29], v[26:27] nt
	s_nop 0
	flat_load_dwordx4 v[30:33], v[30:31] nt
	s_nop 0
	flat_load_dwordx4 v[34:37], v[34:35] nt
	s_nop 0
	flat_load_dwordx4 v[38:41], v[38:39] nt
	v_addc_co_u32_e32 v43, vcc, 0, v59, vcc
	v_add_co_u32_e32 v46, vcc, s38, v58
	s_nop 1
	v_addc_co_u32_e32 v47, vcc, 0, v59, vcc
	v_add_co_u32_e32 v50, vcc, s39, v58
	flat_load_dwordx4 v[42:45], v[42:43] nt
	s_nop 0
	flat_load_dwordx4 v[46:49], v[46:47] nt
	v_addc_co_u32_e32 v51, vcc, 0, v59, vcc
	v_add_co_u32_e32 v54, vcc, s4, v58
	s_mov_b32 s4, 0x380000
	s_nop 0
	v_addc_co_u32_e32 v55, vcc, 0, v59, vcc
	v_add_co_u32_e32 v60, vcc, s4, v58
	s_mov_b32 s4, 0x3c0000
	s_nop 0
	v_addc_co_u32_e32 v61, vcc, 0, v59, vcc
	v_add_co_u32_e32 v62, vcc, s4, v58
	flat_load_dwordx4 v[50:53], v[50:51] nt
	s_nop 0
	flat_load_dwordx4 v[54:57], v[54:55] nt
	v_addc_co_u32_e32 v63, vcc, 0, v59, vcc
	flat_load_dwordx4 v[58:61], v[60:61] nt
	s_nop 0
	flat_load_dwordx4 v[62:65], v[62:63] nt
	s_mul_i32 s4, s24, 0x4400
	s_add_i32 s11, s4, 0
	s_add_u32 s8, s33, s8
	s_addc_u32 s9, s60, s9
	s_lshl_b64 s[0:1], s[0:1], 1
	s_add_u32 s0, s8, s0
	s_movk_i32 s8, 0x110
	v_mul_lo_u32 v66, v150, s8
	v_add3_u32 v151, s11, v155, v66
	v_mul_u32_u24_e32 v248, 0x770, v150
	v_add_u32_e32 v151, v151, v248
	v_lshlrev_b32_e32 v66, 3, v134
	v_and_b32_e32 v153, 56, v66
	v_lshlrev_b32_e32 v66, 13, v152
	v_lshl_or_b32 v144, v153, 1, v66
	v_mul_u32_u24_e32 v66, 0x110, v153
	v_cmp_ne_u64_e64 s[4:5], 0, v[142:143]
	s_addc_u32 s1, s9, s1
	v_add3_u32 v154, s11, v66, v67
	v_mul_u32_u24_e32 v248, 238, v153
	v_sub_u32_e32 v154, v154, v248
	s_add_i32 s41, s10, 0x1000
	s_branch .LBB0_458
